# flash A loop softmax/PV hand-scheduled (max3 tree, interleaved q-fragments, direct V quads); phase_norm issues all gain/scale/shift loads with the row loads
# speedup vs baseline: 1.0467x; 1.0122x over previous
.LBB0_118:
	v_lshl_add_u64 v[32:33], v[18:19], 0, v[8:9]
	global_load_dwordx4 v[18:21], v[32:33], off
	global_load_dwordx4 v[24:27], v[32:33], off offset:1024
	global_load_dwordx4 v[28:31], v[32:33], off offset:2048
	s_nop 0
	global_load_dwordx4 v[32:35], v[32:33], off offset:3072
	v_cmp_lt_i32_e32 vcc, s38, v1
	s_movk_i32 s0, 0x6000
	v_ashrrev_i32_e32 v3, 31, v2
	v_cndmask_b32_e32 v1, 16, v22, vcc
	v_mad_i64_i32 v[22:23], s[0:1], v1, s0, v[16:17]
	s_mov_b64 s[0:1], 0x1000
	s_nop 0
	v_lshl_add_u64 v[48:49], v[22:23], 0, s[0:1]
	v_lshl_add_u64 v[36:37], v[48:49], 0, v[8:9]
	v_lshl_add_u64 v[50:51], v[22:23], 0, v[8:9]
	global_load_dwordx4 v[84:87], v[36:37], off
	global_load_dwordx4 v[68:71], v[4:5], off
	global_load_dwordx4 v[100:103], v[50:51], off
	global_load_dwordx4 v[88:91], v[36:37], off offset:1024
	global_load_dwordx4 v[72:75], v[4:5], off offset:1024
	global_load_dwordx4 v[104:107], v[50:51], off offset:1024
	global_load_dwordx4 v[92:95], v[36:37], off offset:2048
	global_load_dwordx4 v[76:79], v[4:5], off offset:2048
	global_load_dwordx4 v[108:111], v[50:51], off offset:2048
	global_load_dwordx4 v[96:99], v[36:37], off offset:3072
	global_load_dwordx4 v[80:83], v[4:5], off offset:3072
	global_load_dwordx4 v[112:115], v[50:51], off offset:3072
	v_lshlrev_b64 v[22:23], 11, v[2:3]
	v_lshl_add_u64 v[52:53], v[6:7], 0, v[22:23]
	v_add_u32_e32 v2, s65, v2
	s_movk_i32 s0, 0x47ff
	s_waitcnt vmcnt(12)
	v_pk_mul_f32 v[54:55], v[18:19], v[18:19]
	v_pk_mul_f32 v[58:59], v[24:25], v[24:25]
	v_pk_mul_f32 v[22:23], v[20:21], v[20:21]
	v_pk_mul_f32 v[56:57], v[26:27], v[26:27]
	v_pk_mul_f32 v[62:63], v[28:29], v[28:29]
	v_add_f32_e32 v1, v58, v59
	v_add_f32_e32 v3, v54, v55
	v_pk_mul_f32 v[60:61], v[30:31], v[30:31]
	v_pk_mul_f32 v[66:67], v[32:33], v[32:33]
	v_add_f32_e32 v54, v62, v63
	v_add_f32_e32 v1, v1, v56
	v_add_f32_e32 v3, v3, v22
	v_pk_mul_f32 v[64:65], v[34:35], v[34:35]
	v_add_f32_e32 v55, v66, v67
	v_add_f32_e32 v22, v54, v60
	v_add_f32_e32 v1, v1, v57
	v_add_f32_e32 v3, v3, v23
	v_add_f32_e32 v54, v55, v64
	v_add_f32_e32 v22, v22, v61
	v_add_f32_e32 v1, v3, v1
	v_add_f32_e32 v23, v54, v65
	v_add_f32_e32 v1, v1, v22
	v_add_f32_e32 v1, v1, v23
	s_nop 1
	v_add_f32_dpp v1, v1, v1 quad_perm:[1,0,3,2] row_mask:0xf bank_mask:0xf bound_ctrl:1
	s_nop 1
	v_add_f32_dpp v1, v1, v1 quad_perm:[2,3,0,1] row_mask:0xf bank_mask:0xf bound_ctrl:1
	s_nop 1
	v_add_f32_dpp v1, v1, v1 row_half_mirror row_mask:0xf bank_mask:0xf bound_ctrl:1
	s_nop 1
	v_add_f32_dpp v1, v1, v1 row_mirror row_mask:0xf bank_mask:0xf bound_ctrl:1
	v_mov_b32_e32 v3, v1
	s_nop 1
	v_permlane16_swap_b32_e32 v1, v3
	v_add_f32_e32 v1, v1, v3
	v_mov_b32_e32 v3, v1
	s_nop 1
	v_permlane32_swap_b32_e32 v1, v3
	v_add_f32_e32 v1, v1, v3
	v_fmamk_f32 v1, v1, 0x3a800000, v235
	v_mul_f32_e32 v3, 0x4b800000, v1
	v_cmp_gt_f32_e32 vcc, s8, v1
	s_nop 1
	v_cndmask_b32_e32 v1, v1, v3, vcc
	v_rsq_f32_e32 v1, v1
	s_nop 0
	v_mul_f32_e32 v3, 0x45800000, v1
	v_cndmask_b32_e32 v54, v1, v3, vcc
	v_pk_mul_f32 v[18:19], v[18:19], v[54:55] op_sel_hi:[1,0]
	v_pk_mul_f32 v[20:21], v[20:21], v[54:55] op_sel_hi:[1,0]
	s_waitcnt vmcnt(9)
	v_pk_mul_f32 v[18:19], v[68:69], v[18:19]
	v_pk_mul_f32 v[20:21], v[70:71], v[20:21]
	v_pk_add_f32 v[84:85], v[84:85], 1.0 op_sel_hi:[1,0]
	v_pk_add_f32 v[86:87], v[86:87], 1.0 op_sel_hi:[1,0]
	v_pk_fma_f32 v[18:19], v[84:85], v[18:19], v[100:101]
	v_pk_fma_f32 v[20:21], v[86:87], v[20:21], v[102:103]
	v_cvt_pk_bf16_f32 v18, v18, v19
	v_cvt_pk_bf16_f32 v19, v20, v21
	global_store_dwordx2 v[52:53], v[18:19], off
	v_pk_mul_f32 v[24:25], v[24:25], v[54:55] op_sel_hi:[1,0]
	v_pk_mul_f32 v[26:27], v[26:27], v[54:55] op_sel_hi:[1,0]
	s_waitcnt vmcnt(7)
	v_pk_mul_f32 v[24:25], v[72:73], v[24:25]
	v_pk_mul_f32 v[26:27], v[74:75], v[26:27]
	v_pk_add_f32 v[88:89], v[88:89], 1.0 op_sel_hi:[1,0]
	v_pk_add_f32 v[90:91], v[90:91], 1.0 op_sel_hi:[1,0]
	v_pk_fma_f32 v[24:25], v[88:89], v[24:25], v[104:105]
	v_pk_fma_f32 v[26:27], v[90:91], v[26:27], v[106:107]
	v_cvt_pk_bf16_f32 v24, v24, v25
	v_cvt_pk_bf16_f32 v25, v26, v27
	global_store_dwordx2 v[52:53], v[24:25], off offset:512
	v_pk_mul_f32 v[28:29], v[28:29], v[54:55] op_sel_hi:[1,0]
	v_pk_mul_f32 v[30:31], v[30:31], v[54:55] op_sel_hi:[1,0]
	s_waitcnt vmcnt(5)
	v_pk_mul_f32 v[28:29], v[76:77], v[28:29]
	v_pk_mul_f32 v[30:31], v[78:79], v[30:31]
	v_pk_add_f32 v[92:93], v[92:93], 1.0 op_sel_hi:[1,0]
	v_pk_add_f32 v[94:95], v[94:95], 1.0 op_sel_hi:[1,0]
	v_pk_fma_f32 v[28:29], v[92:93], v[28:29], v[108:109]
	v_pk_fma_f32 v[30:31], v[94:95], v[30:31], v[110:111]
	v_cvt_pk_bf16_f32 v28, v28, v29
	v_cvt_pk_bf16_f32 v29, v30, v31
	global_store_dwordx2 v[52:53], v[28:29], off offset:1024
	v_pk_mul_f32 v[32:33], v[32:33], v[54:55] op_sel_hi:[1,0]
	v_pk_mul_f32 v[34:35], v[34:35], v[54:55] op_sel_hi:[1,0]
	s_waitcnt vmcnt(3)
	v_pk_mul_f32 v[32:33], v[80:81], v[32:33]
	v_pk_mul_f32 v[34:35], v[82:83], v[34:35]
	v_pk_add_f32 v[96:97], v[96:97], 1.0 op_sel_hi:[1,0]
	v_pk_add_f32 v[98:99], v[98:99], 1.0 op_sel_hi:[1,0]
	v_pk_fma_f32 v[32:33], v[96:97], v[32:33], v[112:113]
	v_pk_fma_f32 v[34:35], v[98:99], v[34:35], v[114:115]
	v_cvt_pk_bf16_f32 v32, v32, v33
	v_cvt_pk_bf16_f32 v33, v34, v35
	global_store_dwordx2 v[52:53], v[32:33], off offset:1536
	v_cmp_lt_i32_e32 vcc, s0, v2
	s_or_b64 s[12:13], vcc, s[12:13]
	s_andn2_b64 exec, exec, s[12:13]
	s_cbranch_execz .LBB0_130

.LBB0_567:
	s_lshl_b32 s14, s28, 14
	s_add_i32 s14, s14, 0
	v_add_u32_e32 v1, s14, v129
	v_add_u32_e32 v2, s14, v130
	ds_read_b128 v[52:55], v1
	ds_read_b128 v[56:59], v1 offset:2048
	ds_read_b128 v[60:63], v2
	ds_read_b128 v[64:67], v2 offset:2048
	ds_read_b128 v[68:71], v1 offset:4096
	ds_read_b128 v[72:75], v1 offset:6144
	ds_read_b128 v[76:79], v2 offset:4096
	ds_read_b128 v[80:83], v2 offset:6144
	s_waitcnt lgkmcnt(0)
	v_mfma_f32_16x16x32_bf16 v[84:87], v[52:55], v[4:7], 0
	v_mfma_f32_16x16x32_bf16 v[52:55], v[52:55], v[12:15], 0
	v_mfma_f32_16x16x32_bf16 v[96:99], v[60:63], v[16:19], v[52:55]
	v_mfma_f32_16x16x32_bf16 v[52:55], v[56:59], v[4:7], 0
	v_mfma_f32_16x16x32_bf16 v[56:59], v[56:59], v[12:15], 0
	v_mfma_f32_16x16x32_bf16 v[108:111], v[64:67], v[8:11], v[52:55]
	v_mfma_f32_16x16x32_bf16 v[92:95], v[64:67], v[16:19], v[56:59]
	v_mfma_f32_16x16x32_bf16 v[52:55], v[68:71], v[4:7], 0
	v_mfma_f32_16x16x32_bf16 v[56:59], v[68:71], v[12:15], 0
	v_mfma_f32_16x16x32_bf16 v[104:107], v[76:79], v[8:11], v[52:55]
	v_mfma_f32_16x16x32_bf16 v[68:71], v[76:79], v[16:19], v[56:59]
	v_mfma_f32_16x16x32_bf16 v[52:55], v[72:75], v[4:7], 0
	v_mfma_f32_16x16x32_bf16 v[56:59], v[72:75], v[12:15], 0
	v_mfma_f32_16x16x32_bf16 v[112:115], v[60:63], v[8:11], v[84:87]
	v_mfma_f32_16x16x32_bf16 v[100:103], v[80:83], v[8:11], v[52:55]
	v_mfma_f32_16x16x32_bf16 v[56:59], v[80:83], v[16:19], v[56:59]
	v_add_u32_e32 v1, s14, v131
	v_add_u32_e32 v2, s14, v132
	ds_read_b64 v[88:89], v1 offset:8192
	ds_read_b64 v[90:91], v2 offset:8192
	ds_read_b64 v[84:85], v1 offset:10240
	ds_read_b64 v[86:87], v2 offset:10240
	ds_read_b64 v[80:81], v1 offset:12288
	ds_read_b64 v[82:83], v2 offset:12288
	ds_read_b64 v[76:77], v1 offset:14336
	ds_read_b64 v[78:79], v2 offset:14336
	v_add_u32_e32 v1, s14, v133
	v_add_u32_e32 v2, s14, v134
	ds_read_b64 v[72:73], v1 offset:8192
	ds_read_b64 v[74:75], v2 offset:8192
	ds_read_b64 v[64:65], v1 offset:10240
	ds_read_b64 v[66:67], v2 offset:10240
	ds_read_b64 v[60:61], v1 offset:12288
	ds_read_b64 v[62:63], v2 offset:12288
	ds_read_b64 v[52:53], v1 offset:14336
	ds_read_b64 v[54:55], v2 offset:14336
	v_max3_f32 v1, v112, v113, v114
	v_max3_f32 v2, v96, v97, v98
	v_max3_f32 v1, v1, v115, v108
	v_max3_f32 v2, v2, v99, v92
	v_max3_f32 v1, v1, v109, v110
	v_max3_f32 v2, v2, v93, v94
	v_max3_f32 v1, v1, v111, v104
	v_max3_f32 v2, v2, v95, v68
	v_max3_f32 v1, v1, v105, v106
	v_max3_f32 v2, v2, v69, v70
	v_max3_f32 v1, v1, v107, v100
	v_max3_f32 v2, v2, v71, v56
	v_max3_f32 v1, v1, v101, v102
	v_max3_f32 v2, v2, v57, v58
	v_max_f32_e32 v1, v1, v103
	v_max_f32_e32 v2, v2, v59
	v_mov_b32_e32 v3, v1
	v_mov_b32_e32 v138, v2
	s_nop 0
	v_permlane16_swap_b32_e32 v1, v3
	v_permlane16_swap_b32_e32 v2, v138
	v_max_f32_e32 v1, v1, v3
	v_max_f32_e32 v2, v2, v138
	v_mov_b32_e32 v3, v1
	v_mov_b32_e32 v138, v2
	s_nop 0
	v_permlane32_swap_b32_e32 v1, v3
	v_permlane32_swap_b32_e32 v2, v138
	v_max_f32_e32 v1, v1, v3
	v_max_f32_e32 v2, v2, v138
	v_mul_f32_e32 v1, s4, v1
	v_mul_f32_e32 v2, s4, v2
	v_max_f32_e32 v1, v137, v1
	v_max_f32_e32 v2, v136, v2
	v_cmp_gt_f32_e32 vcc, v1, v137
	v_cmp_gt_f32_e64 s[14:15], v2, v136
	s_nop 1
	s_or_b64 s[14:15], vcc, s[14:15]
	s_cbranch_scc0 .Lfa_a_norescale
	v_sub_f32_e32 v138, v137, v1
	v_exp_f32_e32 v138, v138
	v_sub_f32_e32 v3, v136, v2
	v_exp_f32_e32 v3, v3
	v_mul_f32_e32 v135, v135, v138
	v_pk_mul_f32 v[50:51], v[50:51], v[138:139] op_sel_hi:[1,0]
	v_pk_mul_f32 v[48:49], v[48:49], v[138:139] op_sel_hi:[1,0]
	v_pk_mul_f32 v[46:47], v[46:47], v[138:139] op_sel_hi:[1,0]
	v_pk_mul_f32 v[44:45], v[44:45], v[138:139] op_sel_hi:[1,0]
	v_pk_mul_f32 v[42:43], v[42:43], v[138:139] op_sel_hi:[1,0]
	v_pk_mul_f32 v[40:41], v[40:41], v[138:139] op_sel_hi:[1,0]
	v_pk_mul_f32 v[38:39], v[38:39], v[138:139] op_sel_hi:[1,0]
	v_pk_mul_f32 v[36:37], v[36:37], v[138:139] op_sel_hi:[1,0]
	v_mov_b32_e32 v138, v3
	v_mul_f32_e32 v128, v128, v3
	v_pk_mul_f32 v[34:35], v[34:35], v[138:139] op_sel_hi:[1,0]
	v_pk_mul_f32 v[32:33], v[32:33], v[138:139] op_sel_hi:[1,0]
	v_pk_mul_f32 v[30:31], v[30:31], v[138:139] op_sel_hi:[1,0]
	v_pk_mul_f32 v[28:29], v[28:29], v[138:139] op_sel_hi:[1,0]
	v_pk_mul_f32 v[26:27], v[26:27], v[138:139] op_sel_hi:[1,0]
	v_pk_mul_f32 v[24:25], v[24:25], v[138:139] op_sel_hi:[1,0]
	v_pk_mul_f32 v[22:23], v[22:23], v[138:139] op_sel_hi:[1,0]
	v_pk_mul_f32 v[20:21], v[20:21], v[138:139] op_sel_hi:[1,0]
.Lfa_a_norescale:
	v_fma_f32 v112, v112, s4, -v1
	v_exp_f32_e32 v112, v112
	v_fma_f32 v96, v96, s4, -v2
	v_exp_f32_e32 v96, v96
	v_fma_f32 v113, v113, s4, -v1
	v_exp_f32_e32 v113, v113
	v_fma_f32 v97, v97, s4, -v2
	v_exp_f32_e32 v97, v97
	v_fma_f32 v114, v114, s4, -v1
	v_exp_f32_e32 v114, v114
	v_fma_f32 v98, v98, s4, -v2
	v_exp_f32_e32 v98, v98
	v_fma_f32 v115, v115, s4, -v1
	v_exp_f32_e32 v115, v115
	v_fma_f32 v99, v99, s4, -v2
	v_exp_f32_e32 v99, v99
	v_fma_f32 v108, v108, s4, -v1
	v_exp_f32_e32 v108, v108
	v_fma_f32 v92, v92, s4, -v2
	v_exp_f32_e32 v92, v92
	v_fma_f32 v109, v109, s4, -v1
	v_exp_f32_e32 v109, v109
	v_fma_f32 v93, v93, s4, -v2
	v_exp_f32_e32 v93, v93
	v_fma_f32 v110, v110, s4, -v1
	v_exp_f32_e32 v110, v110
	v_fma_f32 v94, v94, s4, -v2
	v_exp_f32_e32 v94, v94
	v_fma_f32 v111, v111, s4, -v1
	v_exp_f32_e32 v111, v111
	v_fma_f32 v95, v95, s4, -v2
	v_exp_f32_e32 v95, v95
	v_pk_add_f32 v[138:139], v[112:113], v[114:115]
	v_pk_add_f32 v[138:139], v[138:139], v[108:109]
	v_pk_add_f32 v[138:139], v[138:139], v[110:111]
	v_add_f32_e32 v138, v138, v139
	v_add_f32_e32 v135, v135, v138
	v_pk_add_f32 v[138:139], v[96:97], v[98:99]
	v_pk_add_f32 v[138:139], v[138:139], v[92:93]
	v_pk_add_f32 v[138:139], v[138:139], v[94:95]
	v_add_f32_e32 v138, v138, v139
	v_add_f32_e32 v128, v128, v138
	v_cvt_pk_bf16_f32 v112, v112, v113
	v_cvt_pk_bf16_f32 v113, v114, v115
	v_cvt_pk_bf16_f32 v114, v108, v109
	v_cvt_pk_bf16_f32 v115, v110, v111
	v_cvt_pk_bf16_f32 v96, v96, v97
	v_cvt_pk_bf16_f32 v97, v98, v99
	v_cvt_pk_bf16_f32 v98, v92, v93
	v_cvt_pk_bf16_f32 v99, v94, v95
	s_waitcnt lgkmcnt(0)
	s_add_i32 s14, s28, 1
	s_cmp_lg_u32 s14, 4
	s_cselect_b32 s28, s14, 0
	v_mfma_f32_16x16x32_bf16 v[48:51], v[88:91], v[112:115], v[48:51]
	v_fma_f32 v104, v104, s4, -v1
	v_exp_f32_e32 v104, v104
	v_fma_f32 v68, v68, s4, -v2
	v_exp_f32_e32 v68, v68
	v_mfma_f32_16x16x32_bf16 v[32:35], v[88:91], v[96:99], v[32:35]
	v_fma_f32 v105, v105, s4, -v1
	v_exp_f32_e32 v105, v105
	v_fma_f32 v69, v69, s4, -v2
	v_exp_f32_e32 v69, v69
	v_mfma_f32_16x16x32_bf16 v[44:47], v[84:87], v[112:115], v[44:47]
	v_fma_f32 v106, v106, s4, -v1
	v_exp_f32_e32 v106, v106
	v_fma_f32 v70, v70, s4, -v2
	v_exp_f32_e32 v70, v70
	v_mfma_f32_16x16x32_bf16 v[28:31], v[84:87], v[96:99], v[28:31]
	v_fma_f32 v107, v107, s4, -v1
	v_exp_f32_e32 v107, v107
	v_fma_f32 v71, v71, s4, -v2
	v_exp_f32_e32 v71, v71
	v_mfma_f32_16x16x32_bf16 v[40:43], v[80:83], v[112:115], v[40:43]
	v_fma_f32 v100, v100, s4, -v1
	v_exp_f32_e32 v100, v100
	v_fma_f32 v56, v56, s4, -v2
	v_exp_f32_e32 v56, v56
	v_mfma_f32_16x16x32_bf16 v[20:23], v[80:83], v[96:99], v[20:23]
	v_fma_f32 v101, v101, s4, -v1
	v_exp_f32_e32 v101, v101
	v_fma_f32 v57, v57, s4, -v2
	v_exp_f32_e32 v57, v57
	v_mfma_f32_16x16x32_bf16 v[36:39], v[76:79], v[112:115], v[36:39]
	v_fma_f32 v102, v102, s4, -v1
	v_exp_f32_e32 v102, v102
	v_fma_f32 v58, v58, s4, -v2
	v_exp_f32_e32 v58, v58
	v_mfma_f32_16x16x32_bf16 v[24:27], v[76:79], v[96:99], v[24:27]
	v_fma_f32 v103, v103, s4, -v1
	v_exp_f32_e32 v103, v103
	v_fma_f32 v59, v59, s4, -v2
	v_exp_f32_e32 v59, v59
	v_pk_add_f32 v[138:139], v[104:105], v[106:107]
	v_pk_add_f32 v[138:139], v[138:139], v[100:101]
	v_pk_add_f32 v[138:139], v[138:139], v[102:103]
	v_add_f32_e32 v138, v138, v139
	v_add_f32_e32 v135, v135, v138
	v_pk_add_f32 v[138:139], v[68:69], v[70:71]
	v_pk_add_f32 v[138:139], v[138:139], v[56:57]
	v_pk_add_f32 v[138:139], v[138:139], v[58:59]
	v_add_f32_e32 v138, v138, v139
	v_add_f32_e32 v128, v128, v138
	v_cvt_pk_bf16_f32 v104, v104, v105
	v_cvt_pk_bf16_f32 v105, v106, v107
	v_cvt_pk_bf16_f32 v106, v100, v101
	v_cvt_pk_bf16_f32 v107, v102, v103
	v_cvt_pk_bf16_f32 v68, v68, v69
	v_cvt_pk_bf16_f32 v69, v70, v71
	v_cvt_pk_bf16_f32 v70, v56, v57
	v_cvt_pk_bf16_f32 v71, v58, v59
	s_add_u32 s12, s12, 0x80
	s_addc_u32 s13, s13, 0
	s_add_u32 s26, s26, s7
	s_addc_u32 s27, s27, 0
	s_add_i32 s18, s18, 1
	s_add_i32 s30, s30, -1
	v_mfma_f32_16x16x32_bf16 v[48:51], v[72:75], v[104:107], v[48:51]
	v_mfma_f32_16x16x32_bf16 v[32:35], v[72:75], v[68:71], v[32:35]
	v_mfma_f32_16x16x32_bf16 v[44:47], v[64:67], v[104:107], v[44:47]
	v_mfma_f32_16x16x32_bf16 v[28:31], v[64:67], v[68:71], v[28:31]
	v_mfma_f32_16x16x32_bf16 v[40:43], v[60:63], v[104:107], v[40:43]
	v_mfma_f32_16x16x32_bf16 v[20:23], v[60:63], v[68:71], v[20:23]
	v_mfma_f32_16x16x32_bf16 v[36:39], v[52:55], v[104:107], v[36:39]
	v_mfma_f32_16x16x32_bf16 v[24:27], v[52:55], v[68:71], v[24:27]
	s_cmp_lg_u32 s6, s12
	s_cbranch_scc0 .LBB0_573
	v_mov_b32_e32 v137, v1
	v_mov_b32_e32 v136, v2
	s_cmp_lt_i32 s30, 2
	s_mov_b64 s[14:15], -1
	s_cbranch_scc1 .LBB0_558
	s_branch .LBB0_563

.LBB0_1077:
	s_or_b64 exec, exec, s[28:29]
	v_ashrrev_i32_e32 v17, 31, v16
	v_lshlrev_b64 v[16:17], 12, v[16:17]
	v_lshl_add_u64 v[16:17], v[18:19], 0, v[16:17]
	v_mov_b32_e32 v9, v0
	v_lshl_add_u64 v[28:29], v[16:17], 0, v[8:9]
	global_load_dwordx4 v[16:19], v[28:29], off
	global_load_dwordx4 v[20:23], v[28:29], off offset:1024
	global_load_dwordx4 v[24:27], v[28:29], off offset:2048
	s_nop 0
	global_load_dwordx4 v[28:31], v[28:29], off offset:3072
	v_readlane_b32 s0, v252, 34
	v_ashrrev_i32_e32 v3, 31, v2
	v_lshlrev_b64 v[48:49], 11, v[2:3]
	v_add_u32_e32 v1, s0, v1
	v_cndmask_b32_e64 v1, v1, 16, vcc
	v_mul_hi_i32_i24_e32 v33, 0x6000, v1
	v_mul_i32_i24_e32 v32, 0x6000, v1
	v_lshl_add_u64 v[40:41], s[12:13], 0, v[32:33]
	s_mov_b64 s[0:1], 0x1000
	v_lshl_add_u64 v[44:45], v[40:41], 0, s[0:1]
	v_lshl_add_u64 v[32:33], v[44:45], 0, v[8:9]
	v_lshl_add_u64 v[46:47], v[40:41], 0, v[8:9]
	global_load_dwordx4 v[84:87], v[32:33], off
	global_load_dwordx4 v[68:71], v[4:5], off
	global_load_dwordx4 v[100:103], v[46:47], off
	global_load_dwordx4 v[88:91], v[32:33], off offset:1024
	global_load_dwordx4 v[72:75], v[4:5], off offset:1024
	global_load_dwordx4 v[104:107], v[46:47], off offset:1024
	global_load_dwordx4 v[92:95], v[32:33], off offset:2048
	global_load_dwordx4 v[76:79], v[4:5], off offset:2048
	global_load_dwordx4 v[108:111], v[46:47], off offset:2048
	global_load_dwordx4 v[96:99], v[32:33], off offset:3072
	global_load_dwordx4 v[80:83], v[4:5], off offset:3072
	global_load_dwordx4 v[112:115], v[46:47], off offset:3072
	s_mov_b32 s0, 0x800000
	v_lshl_add_u64 v[48:49], v[6:7], 0, v[48:49]
	v_mov_b32_e32 v11, v0
	v_mov_b32_e32 v15, v0
	s_waitcnt vmcnt(12)
	v_pk_mul_f32 v[52:53], v[16:17], v[16:17]
	v_pk_mul_f32 v[56:57], v[20:21], v[20:21]
	v_pk_mul_f32 v[50:51], v[18:19], v[18:19]
	v_pk_mul_f32 v[54:55], v[22:23], v[22:23]
	v_pk_mul_f32 v[60:61], v[24:25], v[24:25]
	v_add_f32_e32 v1, v56, v57
	v_add_f32_e32 v3, v52, v53
	v_pk_mul_f32 v[58:59], v[26:27], v[26:27]
	v_pk_mul_f32 v[64:65], v[28:29], v[28:29]
	v_add_f32_e32 v9, v60, v61
	v_add_f32_e32 v1, v1, v54
	v_add_f32_e32 v3, v3, v50
	v_pk_mul_f32 v[62:63], v[30:31], v[30:31]
	v_add_f32_e32 v13, v64, v65
	v_add_f32_e32 v9, v9, v58
	v_add_f32_e32 v1, v1, v55
	v_add_f32_e32 v3, v3, v51
	v_add_f32_e32 v13, v13, v62
	v_add_f32_e32 v9, v9, v59
	v_add_f32_e32 v1, v3, v1
	v_add_f32_e32 v13, v13, v63
	v_add_f32_e32 v1, v1, v9
	v_add_f32_e32 v1, v1, v13
	v_mov_b32_e32 v13, v0
	s_nop 0
	v_add_f32_dpp v1, v1, v1 quad_perm:[1,0,3,2] row_mask:0xf bank_mask:0xf bound_ctrl:1
	s_nop 1
	v_add_f32_dpp v1, v1, v1 quad_perm:[2,3,0,1] row_mask:0xf bank_mask:0xf bound_ctrl:1
	s_nop 1
	v_add_f32_dpp v1, v1, v1 row_half_mirror row_mask:0xf bank_mask:0xf bound_ctrl:1
	s_nop 1
	v_add_f32_dpp v1, v1, v1 row_mirror row_mask:0xf bank_mask:0xf bound_ctrl:1
	v_mov_b32_e32 v3, v1
	s_nop 1
	v_permlane16_swap_b32_e32 v1, v3
	v_add_f32_e32 v1, v1, v3
	v_mov_b32_e32 v3, v1
	s_nop 1
	v_permlane32_swap_b32_e32 v1, v3
	v_add_f32_e32 v1, v1, v3
	v_fmamk_f32 v1, v1, 0x3a800000, v235
	v_mul_f32_e32 v3, 0x4b800000, v1
	v_cmp_gt_f32_e32 vcc, s0, v1
	s_nop 1
	v_cndmask_b32_e32 v1, v1, v3, vcc
	v_rsq_f32_e32 v1, v1
	s_nop 0
	v_mul_f32_e32 v3, 0x45800000, v1
	v_cndmask_b32_e32 v52, v1, v3, vcc
	v_pk_mul_f32 v[16:17], v[16:17], v[52:53] op_sel_hi:[1,0]
	v_pk_mul_f32 v[18:19], v[18:19], v[52:53] op_sel_hi:[1,0]
	s_waitcnt vmcnt(9)
	v_pk_mul_f32 v[16:17], v[68:69], v[16:17]
	v_pk_mul_f32 v[18:19], v[70:71], v[18:19]
	v_pk_add_f32 v[84:85], v[84:85], 1.0 op_sel_hi:[1,0]
	v_pk_add_f32 v[86:87], v[86:87], 1.0 op_sel_hi:[1,0]
	v_pk_fma_f32 v[16:17], v[84:85], v[16:17], v[100:101]
	v_pk_fma_f32 v[18:19], v[86:87], v[18:19], v[102:103]
	v_cvt_pk_bf16_f32 v16, v16, v17
	v_cvt_pk_bf16_f32 v17, v18, v19
	global_store_dwordx2 v[48:49], v[16:17], off
	v_pk_mul_f32 v[20:21], v[20:21], v[52:53] op_sel_hi:[1,0]
	v_pk_mul_f32 v[22:23], v[22:23], v[52:53] op_sel_hi:[1,0]
	s_waitcnt vmcnt(7)
	v_pk_mul_f32 v[20:21], v[72:73], v[20:21]
	v_pk_mul_f32 v[22:23], v[74:75], v[22:23]
	v_pk_add_f32 v[88:89], v[88:89], 1.0 op_sel_hi:[1,0]
	v_pk_add_f32 v[90:91], v[90:91], 1.0 op_sel_hi:[1,0]
	v_pk_fma_f32 v[20:21], v[88:89], v[20:21], v[104:105]
	v_pk_fma_f32 v[22:23], v[90:91], v[22:23], v[106:107]
	v_cvt_pk_bf16_f32 v20, v20, v21
	v_cvt_pk_bf16_f32 v21, v22, v23
	global_store_dwordx2 v[48:49], v[20:21], off offset:512
	v_pk_mul_f32 v[24:25], v[24:25], v[52:53] op_sel_hi:[1,0]
	v_pk_mul_f32 v[26:27], v[26:27], v[52:53] op_sel_hi:[1,0]
	s_waitcnt vmcnt(5)
	v_pk_mul_f32 v[24:25], v[76:77], v[24:25]
	v_pk_mul_f32 v[26:27], v[78:79], v[26:27]
	v_pk_add_f32 v[92:93], v[92:93], 1.0 op_sel_hi:[1,0]
	v_pk_add_f32 v[94:95], v[94:95], 1.0 op_sel_hi:[1,0]
	v_pk_fma_f32 v[24:25], v[92:93], v[24:25], v[108:109]
	v_pk_fma_f32 v[26:27], v[94:95], v[26:27], v[110:111]
	v_cvt_pk_bf16_f32 v24, v24, v25
	v_cvt_pk_bf16_f32 v25, v26, v27
	global_store_dwordx2 v[48:49], v[24:25], off offset:1024
	v_pk_mul_f32 v[28:29], v[28:29], v[52:53] op_sel_hi:[1,0]
	v_pk_mul_f32 v[30:31], v[30:31], v[52:53] op_sel_hi:[1,0]
	s_waitcnt vmcnt(3)
	v_pk_mul_f32 v[28:29], v[80:81], v[28:29]
	v_pk_mul_f32 v[30:31], v[82:83], v[30:31]
	v_pk_add_f32 v[96:97], v[96:97], 1.0 op_sel_hi:[1,0]
	v_pk_add_f32 v[98:99], v[98:99], 1.0 op_sel_hi:[1,0]
	v_pk_fma_f32 v[28:29], v[96:97], v[28:29], v[112:113]
	v_pk_fma_f32 v[30:31], v[98:99], v[30:31], v[114:115]
	v_cvt_pk_bf16_f32 v28, v28, v29
	v_cvt_pk_bf16_f32 v29, v30, v31
	global_store_dwordx2 v[48:49], v[28:29], off offset:1536
